# v98 (gemm_in bf16 store pair widening) + grid-barrier spin loops poll without s_sleep
# baseline (speedup 1.0000x reference)
.Lxb_flag:
	global_load_dword v2, v4, s[6:7] offset:-3584 sc1
	s_waitcnt vmcnt(0)
	v_readfirstlane_b32 s100, v2
	s_cmp_eq_u32 s100, 0x6a3d91c7
	s_cbranch_scc1 .Lxb_flag_ok
	s_nop 3
	s_sub_u32 s101, s101, 1
	s_cmp_lg_u32 s101, 0
	s_cbranch_scc1 .Lxb_flag

.Lxb_cen:
	s_mov_b32 s100, 0
	global_load_dword v2, v4, s[6:7] offset:-2048 sc1
	s_waitcnt vmcnt(0)
	v_readfirstlane_b32 s99, v2
	s_add_u32 s100, s100, s99
	global_load_dword v2, v4, s[6:7] offset:-1920 sc1
	s_waitcnt vmcnt(0)
	v_readfirstlane_b32 s99, v2
	s_add_u32 s100, s100, s99
	global_load_dword v2, v4, s[6:7] offset:-1792 sc1
	s_waitcnt vmcnt(0)
	v_readfirstlane_b32 s99, v2
	s_add_u32 s100, s100, s99
	global_load_dword v2, v4, s[6:7] offset:-1664 sc1
	s_waitcnt vmcnt(0)
	v_readfirstlane_b32 s99, v2
	s_add_u32 s100, s100, s99
	global_load_dword v2, v4, s[6:7] offset:-1536 sc1
	s_waitcnt vmcnt(0)
	v_readfirstlane_b32 s99, v2
	s_add_u32 s100, s100, s99
	global_load_dword v2, v4, s[6:7] offset:-1408 sc1
	s_waitcnt vmcnt(0)
	v_readfirstlane_b32 s99, v2
	s_add_u32 s100, s100, s99
	global_load_dword v2, v4, s[6:7] offset:-1280 sc1
	s_waitcnt vmcnt(0)
	v_readfirstlane_b32 s99, v2
	s_add_u32 s100, s100, s99
	global_load_dword v2, v4, s[6:7] offset:-1152 sc1
	s_waitcnt vmcnt(0)
	v_readfirstlane_b32 s99, v2
	s_add_u32 s100, s100, s99
	s_cmp_eq_u32 s100, s40
	s_cbranch_scc1 .Lxb_cen_done
	s_nop 3
	s_sub_u32 s101, s101, 1
	s_cmp_lg_u32 s101, 0
	s_cbranch_scc1 .Lxb_cen

.Lxb_topspin_s1:
	global_load_dword v3, v4, s[6:7] offset:-3840 sc1
	s_waitcnt vmcnt(0)
	v_readfirstlane_b32 s99, v3
	s_cmp_ge_u32 s99, 1
	s_cbranch_scc1 .Lxb_topdone_s1
	s_nop 3
	s_sub_u32 s101, s101, 1
	s_cmp_lg_u32 s101, 0
	s_cbranch_scc1 .Lxb_topspin_s1

.Lxb_spin_s1:
	global_load_dword v3, v1, s[6:7] offset:128 sc1
	s_waitcnt vmcnt(0)
	v_readfirstlane_b32 s99, v3
	s_cmp_ge_u32 s99, 1
	s_cbranch_scc1 .Lxb_rel_s1
	s_nop 3
	s_sub_u32 s101, s101, 1
	s_cmp_lg_u32 s101, 0
	s_cbranch_scc1 .Lxb_spin_s1

.Lxb_topspin_s2:
	global_load_dword v3, v4, s[6:7] offset:-3840 sc1
	s_waitcnt vmcnt(0)
	v_readfirstlane_b32 s99, v3
	s_cmp_ge_u32 s99, 2
	s_cbranch_scc1 .Lxb_topdone_s2
	s_nop 3
	s_sub_u32 s101, s101, 1
	s_cmp_lg_u32 s101, 0
	s_cbranch_scc1 .Lxb_topspin_s2

.Lxb_spin_s2:
	global_load_dword v3, v1, s[6:7] offset:128 sc1
	s_waitcnt vmcnt(0)
	v_readfirstlane_b32 s99, v3
	s_cmp_ge_u32 s99, 2
	s_cbranch_scc1 .Lxb_rel_s2
	s_nop 3
	s_sub_u32 s101, s101, 1
	s_cmp_lg_u32 s101, 0
	s_cbranch_scc1 .Lxb_spin_s2

.Lxb_topspin_s3:
	global_load_dword v3, v4, s[6:7] offset:-3840 sc1
	s_waitcnt vmcnt(0)
	v_readfirstlane_b32 s99, v3
	s_cmp_ge_u32 s99, 3
	s_cbranch_scc1 .Lxb_topdone_s3
	s_nop 3
	s_sub_u32 s101, s101, 1
	s_cmp_lg_u32 s101, 0
	s_cbranch_scc1 .Lxb_topspin_s3

.Lxb_spin_s3:
	global_load_dword v3, v1, s[6:7] offset:128 sc1
	s_waitcnt vmcnt(0)
	v_readfirstlane_b32 s99, v3
	s_cmp_ge_u32 s99, 3
	s_cbranch_scc1 .Lxb_rel_s3
	s_nop 3
	s_sub_u32 s101, s101, 1
	s_cmp_lg_u32 s101, 0
	s_cbranch_scc1 .Lxb_spin_s3

.Lxb_topspin_s4:
	global_load_dword v3, v4, s[6:7] offset:-3840 sc1
	s_waitcnt vmcnt(0)
	v_readfirstlane_b32 s99, v3
	s_cmp_ge_u32 s99, 4
	s_cbranch_scc1 .Lxb_topdone_s4
	s_nop 3
	s_sub_u32 s101, s101, 1
	s_cmp_lg_u32 s101, 0
	s_cbranch_scc1 .Lxb_topspin_s4

.Lxb_spin_s4:
	global_load_dword v3, v1, s[6:7] offset:128 sc1
	s_waitcnt vmcnt(0)
	v_readfirstlane_b32 s99, v3
	s_cmp_ge_u32 s99, 4
	s_cbranch_scc1 .Lxb_rel_s4
	s_nop 3
	s_sub_u32 s101, s101, 1
	s_cmp_lg_u32 s101, 0
	s_cbranch_scc1 .Lxb_spin_s4

.Lxb_topspin_s5:
	global_load_dword v3, v4, s[6:7] offset:-3840 sc1
	s_waitcnt vmcnt(0)
	v_readfirstlane_b32 s99, v3
	s_cmp_ge_u32 s99, 5
	s_cbranch_scc1 .Lxb_topdone_s5
	s_nop 3
	s_sub_u32 s101, s101, 1
	s_cmp_lg_u32 s101, 0
	s_cbranch_scc1 .Lxb_topspin_s5

.Lxb_spin_s5:
	global_load_dword v3, v1, s[6:7] offset:128 sc1
	s_waitcnt vmcnt(0)
	v_readfirstlane_b32 s99, v3
	s_cmp_ge_u32 s99, 5
	s_cbranch_scc1 .Lxb_rel_s5
	s_nop 3
	s_sub_u32 s101, s101, 1
	s_cmp_lg_u32 s101, 0
	s_cbranch_scc1 .Lxb_spin_s5

.Lxb_topspin_s6:
	global_load_dword v3, v4, s[4:5] offset:-3840 sc1
	s_waitcnt vmcnt(0)
	v_readfirstlane_b32 s99, v3
	s_cmp_ge_u32 s99, 6
	s_cbranch_scc1 .Lxb_topdone_s6
	s_nop 3
	s_sub_u32 s101, s101, 1
	s_cmp_lg_u32 s101, 0
	s_cbranch_scc1 .Lxb_topspin_s6

.Lxb_spin_s6:
	global_load_dword v3, v1, s[4:5] offset:128 sc1
	s_waitcnt vmcnt(0)
	v_readfirstlane_b32 s99, v3
	s_cmp_ge_u32 s99, 6
	s_cbranch_scc1 .Lxb_rel_s6
	s_nop 3
	s_sub_u32 s101, s101, 1
	s_cmp_lg_u32 s101, 0
	s_cbranch_scc1 .Lxb_spin_s6

.Lxb_topspin_s7:
	global_load_dword v3, v4, s[4:5] offset:-3840 sc1
	s_waitcnt vmcnt(0)
	v_readfirstlane_b32 s99, v3
	s_cmp_ge_u32 s99, 7
	s_cbranch_scc1 .Lxb_topdone_s7
	s_nop 3
	s_sub_u32 s101, s101, 1
	s_cmp_lg_u32 s101, 0
	s_cbranch_scc1 .Lxb_topspin_s7

.Lxb_spin_s7:
	global_load_dword v3, v1, s[4:5] offset:128 sc1
	s_waitcnt vmcnt(0)
	v_readfirstlane_b32 s99, v3
	s_cmp_ge_u32 s99, 7
	s_cbranch_scc1 .Lxb_rel_s7
	s_nop 3
	s_sub_u32 s101, s101, 1
	s_cmp_lg_u32 s101, 0
	s_cbranch_scc1 .Lxb_spin_s7

.Lxb_topspin_s8:
	global_load_dword v3, v4, s[6:7] offset:-3840 sc1
	s_waitcnt vmcnt(0)
	v_readfirstlane_b32 s99, v3
	s_cmp_ge_u32 s99, 8
	s_cbranch_scc1 .Lxb_topdone_s8
	s_nop 3
	s_sub_u32 s101, s101, 1
	s_cmp_lg_u32 s101, 0
	s_cbranch_scc1 .Lxb_topspin_s8

.Lxb_spin_s8:
	global_load_dword v3, v1, s[6:7] offset:128 sc1
	s_waitcnt vmcnt(0)
	v_readfirstlane_b32 s99, v3
	s_cmp_ge_u32 s99, 8
	s_cbranch_scc1 .Lxb_rel_s8
	s_nop 3
	s_sub_u32 s101, s101, 1
	s_cmp_lg_u32 s101, 0
	s_cbranch_scc1 .Lxb_spin_s8

.Lxb_topspin_s9:
	global_load_dword v3, v4, s[6:7] offset:-3840 sc1
	s_waitcnt vmcnt(0)
	v_readfirstlane_b32 s99, v3
	s_cmp_ge_u32 s99, 9
	s_cbranch_scc1 .Lxb_topdone_s9
	s_nop 3
	s_sub_u32 s101, s101, 1
	s_cmp_lg_u32 s101, 0
	s_cbranch_scc1 .Lxb_topspin_s9

.Lxb_spin_s9:
	global_load_dword v3, v1, s[6:7] offset:128 sc1
	s_waitcnt vmcnt(0)
	v_readfirstlane_b32 s99, v3
	s_cmp_ge_u32 s99, 9
	s_cbranch_scc1 .Lxb_rel_s9
	s_nop 3
	s_sub_u32 s101, s101, 1
	s_cmp_lg_u32 s101, 0
	s_cbranch_scc1 .Lxb_spin_s9

.Lxb_topspin_s10:
	global_load_dword v3, v4, s[6:7] offset:-3840 sc1
	s_waitcnt vmcnt(0)
	v_readfirstlane_b32 s99, v3
	s_cmp_ge_u32 s99, 10
	s_cbranch_scc1 .Lxb_topdone_s10
	s_nop 3
	s_sub_u32 s101, s101, 1
	s_cmp_lg_u32 s101, 0
	s_cbranch_scc1 .Lxb_topspin_s10

.Lxb_spin_s10:
	global_load_dword v3, v1, s[6:7] offset:128 sc1
	s_waitcnt vmcnt(0)
	v_readfirstlane_b32 s99, v3
	s_cmp_ge_u32 s99, 10
	s_cbranch_scc1 .Lxb_rel_s10
	s_nop 3
	s_sub_u32 s101, s101, 1
	s_cmp_lg_u32 s101, 0
	s_cbranch_scc1 .Lxb_spin_s10

.Lxb_topspin_s11:
	global_load_dword v3, v4, s[6:7] offset:-3840 sc1
	s_waitcnt vmcnt(0)
	v_readfirstlane_b32 s99, v3
	s_cmp_ge_u32 s99, 11
	s_cbranch_scc1 .Lxb_topdone_s11
	s_nop 3
	s_sub_u32 s101, s101, 1
	s_cmp_lg_u32 s101, 0
	s_cbranch_scc1 .Lxb_topspin_s11

.Lxb_spin_s11:
	global_load_dword v3, v1, s[6:7] offset:128 sc1
	s_waitcnt vmcnt(0)
	v_readfirstlane_b32 s99, v3
	s_cmp_ge_u32 s99, 11
	s_cbranch_scc1 .Lxb_rel_s11
	s_nop 3
	s_sub_u32 s101, s101, 1
	s_cmp_lg_u32 s101, 0
	s_cbranch_scc1 .Lxb_spin_s11

.Lxb_topspin_s12:
	global_load_dword v3, v4, s[6:7] offset:-3840 sc1
	s_waitcnt vmcnt(0)
	v_readfirstlane_b32 s99, v3
	s_cmp_ge_u32 s99, 12
	s_cbranch_scc1 .Lxb_topdone_s12
	s_nop 3
	s_sub_u32 s101, s101, 1
	s_cmp_lg_u32 s101, 0
	s_cbranch_scc1 .Lxb_topspin_s12

.Lxb_spin_s12:
	global_load_dword v3, v1, s[6:7] offset:128 sc1
	s_waitcnt vmcnt(0)
	v_readfirstlane_b32 s99, v3
	s_cmp_ge_u32 s99, 12
	s_cbranch_scc1 .Lxb_rel_s12
	s_nop 3
	s_sub_u32 s101, s101, 1
	s_cmp_lg_u32 s101, 0
	s_cbranch_scc1 .Lxb_spin_s12

.Lxb_topspin_s13:
	global_load_dword v3, v4, s[4:5] offset:-3840 sc1
	s_waitcnt vmcnt(0)
	v_readfirstlane_b32 s99, v3
	s_cmp_ge_u32 s99, 13
	s_cbranch_scc1 .Lxb_topdone_s13
	s_nop 3
	s_sub_u32 s101, s101, 1
	s_cmp_lg_u32 s101, 0
	s_cbranch_scc1 .Lxb_topspin_s13

.Lxb_spin_s13:
	global_load_dword v3, v1, s[4:5] offset:128 sc1
	s_waitcnt vmcnt(0)
	v_readfirstlane_b32 s99, v3
	s_cmp_ge_u32 s99, 13
	s_cbranch_scc1 .Lxb_rel_s13
	s_nop 3
	s_sub_u32 s101, s101, 1
	s_cmp_lg_u32 s101, 0
	s_cbranch_scc1 .Lxb_spin_s13

.Lxb_topspin_s14:
	global_load_dword v3, v4, s[4:5] offset:-3840 sc1
	s_waitcnt vmcnt(0)
	v_readfirstlane_b32 s99, v3
	s_cmp_ge_u32 s99, 14
	s_cbranch_scc1 .Lxb_topdone_s14
	s_nop 3
	s_sub_u32 s101, s101, 1
	s_cmp_lg_u32 s101, 0
	s_cbranch_scc1 .Lxb_topspin_s14

.Lxb_spin_s14:
	global_load_dword v3, v1, s[4:5] offset:128 sc1
	s_waitcnt vmcnt(0)
	v_readfirstlane_b32 s99, v3
	s_cmp_ge_u32 s99, 14
	s_cbranch_scc1 .Lxb_rel_s14
	s_nop 3
	s_sub_u32 s101, s101, 1
	s_cmp_lg_u32 s101, 0
	s_cbranch_scc1 .Lxb_spin_s14

.Lxb_topspin_s15:
	global_load_dword v3, v4, s[6:7] offset:-3840 sc1
	s_waitcnt vmcnt(0)
	v_readfirstlane_b32 s99, v3
	s_cmp_ge_u32 s99, 15
	s_cbranch_scc1 .Lxb_topdone_s15
	s_nop 3
	s_sub_u32 s101, s101, 1
	s_cmp_lg_u32 s101, 0
	s_cbranch_scc1 .Lxb_topspin_s15

.Lxb_spin_s15:
	global_load_dword v3, v1, s[6:7] offset:128 sc1
	s_waitcnt vmcnt(0)
	v_readfirstlane_b32 s99, v3
	s_cmp_ge_u32 s99, 15
	s_cbranch_scc1 .Lxb_rel_s15
	s_nop 3
	s_sub_u32 s101, s101, 1
	s_cmp_lg_u32 s101, 0
	s_cbranch_scc1 .Lxb_spin_s15

.Lxb_topspin_s16:
	global_load_dword v3, v4, s[6:7] offset:-3840 sc1
	s_waitcnt vmcnt(0)
	v_readfirstlane_b32 s99, v3
	s_cmp_ge_u32 s99, 16
	s_cbranch_scc1 .Lxb_topdone_s16
	s_nop 3
	s_sub_u32 s101, s101, 1
	s_cmp_lg_u32 s101, 0
	s_cbranch_scc1 .Lxb_topspin_s16

.Lxb_spin_s16:
	global_load_dword v3, v1, s[6:7] offset:128 sc1
	s_waitcnt vmcnt(0)
	v_readfirstlane_b32 s99, v3
	s_cmp_ge_u32 s99, 16
	s_cbranch_scc1 .Lxb_rel_s16
	s_nop 3
	s_sub_u32 s101, s101, 1
	s_cmp_lg_u32 s101, 0
	s_cbranch_scc1 .Lxb_spin_s16

.LBB0_1489:
	s_nop 3
	global_load_dword v2, v0, s[2:3] offset:32 sc1
	s_waitcnt vmcnt(0)
	v_and_b32_e32 v2, 0xffff0000, v2
	v_cmp_ne_u32_e32 vcc, v2, v1
	s_or_b64 s[4:5], vcc, s[4:5]
	s_andn2_b64 exec, exec, s[4:5]
	s_cbranch_execnz .LBB0_1489
